# attention v2 + static prio, hand-written weight conversion, scalar phase-table, hand-written indexer pass-1 loop
# speedup vs baseline: 1.0282x; 1.0010x over previous
.LBB0_25:
	s_mul_hi_i32 s0, s62, 0x88888889
	s_add_i32 s0, s0, s62
	s_lshr_b32 s1, s0, 31
	s_ashr_i32 s0, s0, 3
	s_add_i32 s2, s0, s1
	s_mov_b32 s0, s2
	v_writelane_b32 v252, s0, 29
	s_nop 1
	v_writelane_b32 v252, s1, 30
	s_mul_i32 s0, s2, 15
	s_sub_i32 s2, s62, s0
	s_ashr_i32 s3, s2, 31
	s_cmp_gt_u32 s2, 7
	s_cselect_b32 s3, 1, 0
	s_add_u32 s3, s3, s2
	s_add_i32 s0, s62, 14
	s_cmp_gt_u32 s0, 28
	s_mov_b32 s0, s3
	s_cbranch_scc1 .LBB0_27
	v_readlane_b32 s2, v252, 24
	v_readlane_b32 s3, v252, 25
	s_load_dwordx2 s[2:3], s[2:3], 0x0
	s_branch .LBB0_28

.LBB0_898:
	v_and_b32_e32 v99, 63, v186
	v_lshl_add_u32 v99, v99, 4, s96
	v_add_u32_e32 v141, s96, v73
	v_add_u32_e32 v142, s96, v75
	v_add_u32_e32 v143, s96, v120
	v_add_u32_e32 v144, s96, v121
	v_add_u32_e32 v145, s96, v122
	v_add_u32_e32 v146, s96, v123
	v_add_u32_e32 v147, s96, v124
	s_mov_b32 s0, 0
	ds_read_b128 v[176:179], v99 offset:0
	ds_read_b128 v[180:183], v99 offset:4096
	ds_read_b128 v[230:233], v99 offset:1024
	ds_read_b128 v[234:237], v99 offset:5120
	ds_read_b128 v[238:241], v99 offset:2048
	ds_read_b128 v[242:245], v99 offset:6144
	ds_read_b128 v[246:249], v99 offset:3072
	ds_read_b128 v[50:53], v99 offset:7168
	s_waitcnt lgkmcnt(7)
	v_mfma_f32_32x32x16_bf16 v[0:15], v[34:37], v[176:179], 0
	s_waitcnt lgkmcnt(6)
	v_mfma_f32_32x32x16_bf16 v[160:175], v[34:37], v[180:183], 0
	s_waitcnt vmcnt(3)
	ds_write_b128 v140, v[16:19] offset:8192
	s_add_i32 s1, s0, 5
	s_min_i32 s1, s1, s14
	v_mad_i64_i32 v[184:185], s[2:3], s1, v193, v[116:117]
	global_load_dwordx4 v[16:19], v[184:185], off
	s_waitcnt lgkmcnt(6)
	v_mfma_f32_32x32x16_bf16 v[0:15], v[38:41], v[230:233], v[0:15]
	s_waitcnt lgkmcnt(5)
	v_mfma_f32_32x32x16_bf16 v[160:175], v[38:41], v[234:237], v[160:175]
	s_waitcnt lgkmcnt(4)
	v_mfma_f32_32x32x16_bf16 v[0:15], v[42:45], v[238:241], v[0:15]
	s_waitcnt lgkmcnt(3)
	v_mfma_f32_32x32x16_bf16 v[160:175], v[42:45], v[242:245], v[160:175]
	s_waitcnt lgkmcnt(2)
	v_mfma_f32_32x32x16_bf16 v[0:15], v[46:49], v[246:249], v[0:15]
	s_waitcnt lgkmcnt(1)
	v_mfma_f32_32x32x16_bf16 v[160:175], v[46:49], v[50:53], v[160:175]
	s_waitcnt lgkmcnt(0)
	s_barrier
	s_add_u32 s0, s0, 1
	s_cmp_ge_u32 s0, s13
	s_cbranch_scc1 .Lp1_drain0
.Lp1_c1:
	ds_read_b128 v[176:179], v99 offset:8192
	ds_read_b128 v[180:183], v99 offset:12288
	ds_read_b128 v[230:233], v99 offset:9216
	ds_read_b128 v[234:237], v99 offset:13312
	ds_read_b128 v[238:241], v99 offset:10240
	ds_read_b128 v[242:245], v99 offset:14336
	ds_read_b128 v[246:249], v99 offset:11264
	ds_read_b128 v[50:53], v99 offset:15360
	v_max_i32_e32 v56, 0, v8
	v_max_i32_e32 v57, 0, v0
	v_max_i32_e32 v60, 0, v9
	v_max_i32_e32 v61, 0, v1
	v_max_i32_e32 v64, 0, v10
	v_max_i32_e32 v65, 0, v2
	v_max_i32_e32 v154, 0, v11
	v_max_i32_e32 v155, 0, v3
	v_pk_fma_f32 v[156:157], v[100:101], v[56:57], 0 op_sel_hi:[1,1,0]
	v_pk_fma_f32 v[156:157], v[102:103], v[60:61], v[156:157]
	s_waitcnt lgkmcnt(7)
	v_mfma_f32_32x32x16_bf16 v[198:213], v[34:37], v[176:179], 0
	v_pk_fma_f32 v[156:157], v[104:105], v[64:65], v[156:157]
	v_pk_fma_f32 v[156:157], v[106:107], v[154:155], v[156:157]
	v_max_i32_e32 v56, 0, v12
	v_max_i32_e32 v57, 0, v4
	v_max_i32_e32 v60, 0, v13
	v_max_i32_e32 v61, 0, v5
	v_max_i32_e32 v64, 0, v14
	v_max_i32_e32 v65, 0, v6
	v_max_i32_e32 v154, 0, v15
	s_waitcnt lgkmcnt(6)
	v_mfma_f32_32x32x16_bf16 v[214:229], v[34:37], v[180:183], 0
	s_waitcnt vmcnt(3)
	ds_write_b128 v140, v[20:23]
	s_add_i32 s1, s0, 5
	s_min_i32 s1, s1, s14
	v_mad_i64_i32 v[184:185], s[2:3], s1, v193, v[116:117]
	global_load_dwordx4 v[20:23], v[184:185], off
	v_max_i32_e32 v155, 0, v7
	v_pk_fma_f32 v[156:157], v[108:109], v[56:57], v[156:157]
	v_pk_fma_f32 v[156:157], v[110:111], v[60:61], v[156:157]
	v_pk_fma_f32 v[156:157], v[112:113], v[64:65], v[156:157]
	v_pk_fma_f32 v[156:157], v[114:115], v[154:155], v[156:157]
	v_bfe_u32 v56, v157, 19, 12
	v_bfe_u32 v64, v156, 19, 12
	v_med3_u32 v56, v56, s94, v194
	v_med3_u32 v64, v64, s94, v194
	s_waitcnt lgkmcnt(6)
	v_mfma_f32_32x32x16_bf16 v[198:213], v[38:41], v[230:233], v[198:213]
	v_sub_u32_e32 v57, 0x86f, v56
	v_add_u32_e32 v60, 0xfffffb90, v56
	v_sub_u32_e32 v65, 0x86f, v64
	v_add_u32_e32 v154, 0xfffffb90, v64
	v_cmp_gt_f32_e32 vcc, 0, v157
	s_nop 1
	v_cndmask_b32_e32 v56, v60, v57, vcc
	v_cmp_gt_f32_e32 vcc, 0, v156
	v_lshl_add_u32 v61, v56, 2, v33
	s_waitcnt lgkmcnt(5)
	v_mfma_f32_32x32x16_bf16 v[214:229], v[38:41], v[234:237], v[214:229]
	ds_add_u32 v61, v188
	v_cndmask_b32_e32 v64, v154, v65, vcc
	v_lshl_add_u32 v155, v64, 2, v33
	ds_add_u32 v155, v188 offset:4096
	v_max_i32_e32 v56, 0, v168
	v_max_i32_e32 v57, 0, v160
	v_max_i32_e32 v60, 0, v169
	v_max_i32_e32 v61, 0, v161
	v_max_i32_e32 v64, 0, v170
	s_waitcnt lgkmcnt(6)
	v_mfma_f32_32x32x16_bf16 v[198:213], v[42:45], v[238:241], v[198:213]
	v_max_i32_e32 v65, 0, v162
	v_max_i32_e32 v154, 0, v171
	v_max_i32_e32 v155, 0, v163
	v_pk_fma_f32 v[156:157], v[100:101], v[56:57], 0 op_sel_hi:[1,1,0]
	v_pk_fma_f32 v[156:157], v[102:103], v[60:61], v[156:157]
	v_pk_fma_f32 v[156:157], v[104:105], v[64:65], v[156:157]
	v_pk_fma_f32 v[156:157], v[106:107], v[154:155], v[156:157]
	v_max_i32_e32 v56, 0, v172
	v_max_i32_e32 v57, 0, v164
	s_waitcnt lgkmcnt(5)
	v_mfma_f32_32x32x16_bf16 v[214:229], v[42:45], v[242:245], v[214:229]
	v_max_i32_e32 v60, 0, v173
	v_max_i32_e32 v61, 0, v165
	v_max_i32_e32 v64, 0, v174
	v_max_i32_e32 v65, 0, v166
	v_max_i32_e32 v154, 0, v175
	v_max_i32_e32 v155, 0, v167
	v_pk_fma_f32 v[156:157], v[108:109], v[56:57], v[156:157]
	v_pk_fma_f32 v[156:157], v[110:111], v[60:61], v[156:157]
	v_pk_fma_f32 v[156:157], v[112:113], v[64:65], v[156:157]
	s_waitcnt lgkmcnt(4)
	v_mfma_f32_32x32x16_bf16 v[198:213], v[46:49], v[246:249], v[198:213]
	v_pk_fma_f32 v[156:157], v[114:115], v[154:155], v[156:157]
	v_bfe_u32 v56, v157, 19, 12
	v_bfe_u32 v64, v156, 19, 12
	v_med3_u32 v56, v56, s94, v194
	v_med3_u32 v64, v64, s94, v194
	v_sub_u32_e32 v57, 0x86f, v56
	v_add_u32_e32 v60, 0xfffffb90, v56
	v_sub_u32_e32 v65, 0x86f, v64
	v_add_u32_e32 v154, 0xfffffb90, v64
	s_waitcnt lgkmcnt(3)
	v_mfma_f32_32x32x16_bf16 v[214:229], v[46:49], v[50:53], v[214:229]
	v_cmp_gt_f32_e32 vcc, 0, v157
	s_nop 1
	v_cndmask_b32_e32 v56, v60, v57, vcc
	v_cmp_gt_f32_e32 vcc, 0, v156
	v_lshl_add_u32 v61, v56, 2, v33
	ds_add_u32 v61, v188
	v_cndmask_b32_e32 v64, v154, v65, vcc
	v_lshl_add_u32 v155, v64, 2, v33
	ds_add_u32 v155, v188 offset:4096
	s_waitcnt lgkmcnt(0)
	s_barrier
	s_add_u32 s0, s0, 1
	s_cmp_ge_u32 s0, s13
	s_cbranch_scc1 .Lp1_drain1
.Lp1_c2:
	ds_read_b128 v[176:179], v99 offset:0
	ds_read_b128 v[180:183], v99 offset:4096
	ds_read_b128 v[230:233], v99 offset:1024
	ds_read_b128 v[234:237], v99 offset:5120
	ds_read_b128 v[238:241], v99 offset:2048
	ds_read_b128 v[242:245], v99 offset:6144
	ds_read_b128 v[246:249], v99 offset:3072
	ds_read_b128 v[50:53], v99 offset:7168
	v_max_i32_e32 v56, 0, v206
	v_max_i32_e32 v57, 0, v198
	v_max_i32_e32 v60, 0, v207
	v_max_i32_e32 v61, 0, v199
	v_max_i32_e32 v64, 0, v208
	v_max_i32_e32 v65, 0, v200
	v_max_i32_e32 v154, 0, v209
	v_max_i32_e32 v155, 0, v201
	v_pk_fma_f32 v[156:157], v[100:101], v[56:57], 0 op_sel_hi:[1,1,0]
	v_pk_fma_f32 v[156:157], v[102:103], v[60:61], v[156:157]
	s_waitcnt lgkmcnt(7)
	v_mfma_f32_32x32x16_bf16 v[0:15], v[34:37], v[176:179], 0
	v_pk_fma_f32 v[156:157], v[104:105], v[64:65], v[156:157]
	v_pk_fma_f32 v[156:157], v[106:107], v[154:155], v[156:157]
	v_max_i32_e32 v56, 0, v210
	v_max_i32_e32 v57, 0, v202
	v_max_i32_e32 v60, 0, v211
	v_max_i32_e32 v61, 0, v203
	v_max_i32_e32 v64, 0, v212
	v_max_i32_e32 v65, 0, v204
	v_max_i32_e32 v154, 0, v213
	s_waitcnt lgkmcnt(6)
	v_mfma_f32_32x32x16_bf16 v[160:175], v[34:37], v[180:183], 0
	s_waitcnt vmcnt(3)
	ds_write_b128 v140, v[24:27] offset:8192
	s_add_i32 s1, s0, 5
	s_min_i32 s1, s1, s14
	v_mad_i64_i32 v[184:185], s[2:3], s1, v193, v[116:117]
	global_load_dwordx4 v[24:27], v[184:185], off
	v_max_i32_e32 v155, 0, v205
	v_pk_fma_f32 v[156:157], v[108:109], v[56:57], v[156:157]
	v_pk_fma_f32 v[156:157], v[110:111], v[60:61], v[156:157]
	v_pk_fma_f32 v[156:157], v[112:113], v[64:65], v[156:157]
	v_pk_fma_f32 v[156:157], v[114:115], v[154:155], v[156:157]
	v_bfe_u32 v56, v157, 19, 12
	v_bfe_u32 v64, v156, 19, 12
	v_med3_u32 v56, v56, s94, v194
	v_med3_u32 v64, v64, s94, v194
	s_waitcnt lgkmcnt(6)
	v_mfma_f32_32x32x16_bf16 v[0:15], v[38:41], v[230:233], v[0:15]
	v_sub_u32_e32 v57, 0x86f, v56
	v_add_u32_e32 v60, 0xfffffb90, v56
	v_sub_u32_e32 v65, 0x86f, v64
	v_add_u32_e32 v154, 0xfffffb90, v64
	v_cmp_gt_f32_e32 vcc, 0, v157
	s_nop 1
	v_cndmask_b32_e32 v56, v60, v57, vcc
	v_cmp_gt_f32_e32 vcc, 0, v156
	v_lshl_add_u32 v61, v56, 2, v33
	s_waitcnt lgkmcnt(5)
	v_mfma_f32_32x32x16_bf16 v[160:175], v[38:41], v[234:237], v[160:175]
	ds_add_u32 v61, v188
	v_cndmask_b32_e32 v64, v154, v65, vcc
	v_lshl_add_u32 v155, v64, 2, v33
	ds_add_u32 v155, v188 offset:4096
	v_max_i32_e32 v56, 0, v222
	v_max_i32_e32 v57, 0, v214
	v_max_i32_e32 v60, 0, v223
	v_max_i32_e32 v61, 0, v215
	v_max_i32_e32 v64, 0, v224
	s_waitcnt lgkmcnt(6)
	v_mfma_f32_32x32x16_bf16 v[0:15], v[42:45], v[238:241], v[0:15]
	v_max_i32_e32 v65, 0, v216
	v_max_i32_e32 v154, 0, v225
	v_max_i32_e32 v155, 0, v217
	v_pk_fma_f32 v[156:157], v[100:101], v[56:57], 0 op_sel_hi:[1,1,0]
	v_pk_fma_f32 v[156:157], v[102:103], v[60:61], v[156:157]
	v_pk_fma_f32 v[156:157], v[104:105], v[64:65], v[156:157]
	v_pk_fma_f32 v[156:157], v[106:107], v[154:155], v[156:157]
	v_max_i32_e32 v56, 0, v226
	v_max_i32_e32 v57, 0, v218
	s_waitcnt lgkmcnt(5)
	v_mfma_f32_32x32x16_bf16 v[160:175], v[42:45], v[242:245], v[160:175]
	v_max_i32_e32 v60, 0, v227
	v_max_i32_e32 v61, 0, v219
	v_max_i32_e32 v64, 0, v228
	v_max_i32_e32 v65, 0, v220
	v_max_i32_e32 v154, 0, v229
	v_max_i32_e32 v155, 0, v221
	v_pk_fma_f32 v[156:157], v[108:109], v[56:57], v[156:157]
	v_pk_fma_f32 v[156:157], v[110:111], v[60:61], v[156:157]
	v_pk_fma_f32 v[156:157], v[112:113], v[64:65], v[156:157]
	s_waitcnt lgkmcnt(4)
	v_mfma_f32_32x32x16_bf16 v[0:15], v[46:49], v[246:249], v[0:15]
	v_pk_fma_f32 v[156:157], v[114:115], v[154:155], v[156:157]
	v_bfe_u32 v56, v157, 19, 12
	v_bfe_u32 v64, v156, 19, 12
	v_med3_u32 v56, v56, s94, v194
	v_med3_u32 v64, v64, s94, v194
	v_sub_u32_e32 v57, 0x86f, v56
	v_add_u32_e32 v60, 0xfffffb90, v56
	v_sub_u32_e32 v65, 0x86f, v64
	v_add_u32_e32 v154, 0xfffffb90, v64
	s_waitcnt lgkmcnt(3)
	v_mfma_f32_32x32x16_bf16 v[160:175], v[46:49], v[50:53], v[160:175]
	v_cmp_gt_f32_e32 vcc, 0, v157
	s_nop 1
	v_cndmask_b32_e32 v56, v60, v57, vcc
	v_cmp_gt_f32_e32 vcc, 0, v156
	v_lshl_add_u32 v61, v56, 2, v33
	ds_add_u32 v61, v188
	v_cndmask_b32_e32 v64, v154, v65, vcc
	v_lshl_add_u32 v155, v64, 2, v33
	ds_add_u32 v155, v188 offset:4096
	s_waitcnt lgkmcnt(0)
	s_barrier
	s_add_u32 s0, s0, 1
	s_cmp_ge_u32 s0, s13
	s_cbranch_scc1 .Lp1_drain0
.Lp1_c3:
	ds_read_b128 v[176:179], v99 offset:8192
	ds_read_b128 v[180:183], v99 offset:12288
	ds_read_b128 v[230:233], v99 offset:9216
	ds_read_b128 v[234:237], v99 offset:13312
	ds_read_b128 v[238:241], v99 offset:10240
	ds_read_b128 v[242:245], v99 offset:14336
	ds_read_b128 v[246:249], v99 offset:11264
	ds_read_b128 v[50:53], v99 offset:15360
	v_max_i32_e32 v56, 0, v8
	v_max_i32_e32 v57, 0, v0
	v_max_i32_e32 v60, 0, v9
	v_max_i32_e32 v61, 0, v1
	v_max_i32_e32 v64, 0, v10
	v_max_i32_e32 v65, 0, v2
	v_max_i32_e32 v154, 0, v11
	v_max_i32_e32 v155, 0, v3
	v_pk_fma_f32 v[156:157], v[100:101], v[56:57], 0 op_sel_hi:[1,1,0]
	v_pk_fma_f32 v[156:157], v[102:103], v[60:61], v[156:157]
	s_waitcnt lgkmcnt(7)
	v_mfma_f32_32x32x16_bf16 v[198:213], v[34:37], v[176:179], 0
	v_pk_fma_f32 v[156:157], v[104:105], v[64:65], v[156:157]
	v_pk_fma_f32 v[156:157], v[106:107], v[154:155], v[156:157]
	v_max_i32_e32 v56, 0, v12
	v_max_i32_e32 v57, 0, v4
	v_max_i32_e32 v60, 0, v13
	v_max_i32_e32 v61, 0, v5
	v_max_i32_e32 v64, 0, v14
	v_max_i32_e32 v65, 0, v6
	v_max_i32_e32 v154, 0, v15
	s_waitcnt lgkmcnt(6)
	v_mfma_f32_32x32x16_bf16 v[214:229], v[34:37], v[180:183], 0
	s_waitcnt vmcnt(3)
	ds_write_b128 v140, v[28:31]
	s_add_i32 s1, s0, 5
	s_min_i32 s1, s1, s14
	v_mad_i64_i32 v[184:185], s[2:3], s1, v193, v[116:117]
	global_load_dwordx4 v[28:31], v[184:185], off
	v_max_i32_e32 v155, 0, v7
	v_pk_fma_f32 v[156:157], v[108:109], v[56:57], v[156:157]
	v_pk_fma_f32 v[156:157], v[110:111], v[60:61], v[156:157]
	v_pk_fma_f32 v[156:157], v[112:113], v[64:65], v[156:157]
	v_pk_fma_f32 v[156:157], v[114:115], v[154:155], v[156:157]
	v_bfe_u32 v56, v157, 19, 12
	v_bfe_u32 v64, v156, 19, 12
	v_med3_u32 v56, v56, s94, v194
	v_med3_u32 v64, v64, s94, v194
	s_waitcnt lgkmcnt(6)
	v_mfma_f32_32x32x16_bf16 v[198:213], v[38:41], v[230:233], v[198:213]
	v_sub_u32_e32 v57, 0x86f, v56
	v_add_u32_e32 v60, 0xfffffb90, v56
	v_sub_u32_e32 v65, 0x86f, v64
	v_add_u32_e32 v154, 0xfffffb90, v64
	v_cmp_gt_f32_e32 vcc, 0, v157
	s_nop 1
	v_cndmask_b32_e32 v56, v60, v57, vcc
	v_cmp_gt_f32_e32 vcc, 0, v156
	v_lshl_add_u32 v61, v56, 2, v33
	s_waitcnt lgkmcnt(5)
	v_mfma_f32_32x32x16_bf16 v[214:229], v[38:41], v[234:237], v[214:229]
	ds_add_u32 v61, v188
	v_cndmask_b32_e32 v64, v154, v65, vcc
	v_lshl_add_u32 v155, v64, 2, v33
	ds_add_u32 v155, v188 offset:4096
	v_max_i32_e32 v56, 0, v168
	v_max_i32_e32 v57, 0, v160
	v_max_i32_e32 v60, 0, v169
	v_max_i32_e32 v61, 0, v161
	v_max_i32_e32 v64, 0, v170
	s_waitcnt lgkmcnt(6)
	v_mfma_f32_32x32x16_bf16 v[198:213], v[42:45], v[238:241], v[198:213]
	v_max_i32_e32 v65, 0, v162
	v_max_i32_e32 v154, 0, v171
	v_max_i32_e32 v155, 0, v163
	v_pk_fma_f32 v[156:157], v[100:101], v[56:57], 0 op_sel_hi:[1,1,0]
	v_pk_fma_f32 v[156:157], v[102:103], v[60:61], v[156:157]
	v_pk_fma_f32 v[156:157], v[104:105], v[64:65], v[156:157]
	v_pk_fma_f32 v[156:157], v[106:107], v[154:155], v[156:157]
	v_max_i32_e32 v56, 0, v172
	v_max_i32_e32 v57, 0, v164
	s_waitcnt lgkmcnt(5)
	v_mfma_f32_32x32x16_bf16 v[214:229], v[42:45], v[242:245], v[214:229]
	v_max_i32_e32 v60, 0, v173
	v_max_i32_e32 v61, 0, v165
	v_max_i32_e32 v64, 0, v174
	v_max_i32_e32 v65, 0, v166
	v_max_i32_e32 v154, 0, v175
	v_max_i32_e32 v155, 0, v167
	v_pk_fma_f32 v[156:157], v[108:109], v[56:57], v[156:157]
	v_pk_fma_f32 v[156:157], v[110:111], v[60:61], v[156:157]
	v_pk_fma_f32 v[156:157], v[112:113], v[64:65], v[156:157]
	s_waitcnt lgkmcnt(4)
	v_mfma_f32_32x32x16_bf16 v[198:213], v[46:49], v[246:249], v[198:213]
	v_pk_fma_f32 v[156:157], v[114:115], v[154:155], v[156:157]
	v_bfe_u32 v56, v157, 19, 12
	v_bfe_u32 v64, v156, 19, 12
	v_med3_u32 v56, v56, s94, v194
	v_med3_u32 v64, v64, s94, v194
	v_sub_u32_e32 v57, 0x86f, v56
	v_add_u32_e32 v60, 0xfffffb90, v56
	v_sub_u32_e32 v65, 0x86f, v64
	v_add_u32_e32 v154, 0xfffffb90, v64
	s_waitcnt lgkmcnt(3)
	v_mfma_f32_32x32x16_bf16 v[214:229], v[46:49], v[50:53], v[214:229]
	v_cmp_gt_f32_e32 vcc, 0, v157
	s_nop 1
	v_cndmask_b32_e32 v56, v60, v57, vcc
	v_cmp_gt_f32_e32 vcc, 0, v156
	v_lshl_add_u32 v61, v56, 2, v33
	ds_add_u32 v61, v188
	v_cndmask_b32_e32 v64, v154, v65, vcc
	v_lshl_add_u32 v155, v64, 2, v33
	ds_add_u32 v155, v188 offset:4096
	s_waitcnt lgkmcnt(0)
	s_barrier
	s_add_u32 s0, s0, 1
	s_cmp_ge_u32 s0, s13
	s_cbranch_scc1 .Lp1_drain1
.Lp1_c0:
	ds_read_b128 v[176:179], v99 offset:0
	ds_read_b128 v[180:183], v99 offset:4096
	ds_read_b128 v[230:233], v99 offset:1024
	ds_read_b128 v[234:237], v99 offset:5120
	ds_read_b128 v[238:241], v99 offset:2048
	ds_read_b128 v[242:245], v99 offset:6144
	ds_read_b128 v[246:249], v99 offset:3072
	ds_read_b128 v[50:53], v99 offset:7168
	v_max_i32_e32 v56, 0, v206
	v_max_i32_e32 v57, 0, v198
	v_max_i32_e32 v60, 0, v207
	v_max_i32_e32 v61, 0, v199
	v_max_i32_e32 v64, 0, v208
	v_max_i32_e32 v65, 0, v200
	v_max_i32_e32 v154, 0, v209
	v_max_i32_e32 v155, 0, v201
	v_pk_fma_f32 v[156:157], v[100:101], v[56:57], 0 op_sel_hi:[1,1,0]
	v_pk_fma_f32 v[156:157], v[102:103], v[60:61], v[156:157]
	s_waitcnt lgkmcnt(7)
	v_mfma_f32_32x32x16_bf16 v[0:15], v[34:37], v[176:179], 0
	v_pk_fma_f32 v[156:157], v[104:105], v[64:65], v[156:157]
	v_pk_fma_f32 v[156:157], v[106:107], v[154:155], v[156:157]
	v_max_i32_e32 v56, 0, v210
	v_max_i32_e32 v57, 0, v202
	v_max_i32_e32 v60, 0, v211
	v_max_i32_e32 v61, 0, v203
	v_max_i32_e32 v64, 0, v212
	v_max_i32_e32 v65, 0, v204
	v_max_i32_e32 v154, 0, v213
	s_waitcnt lgkmcnt(6)
	v_mfma_f32_32x32x16_bf16 v[160:175], v[34:37], v[180:183], 0
	s_waitcnt vmcnt(3)
	ds_write_b128 v140, v[16:19] offset:8192
	s_add_i32 s1, s0, 5
	s_min_i32 s1, s1, s14
	v_mad_i64_i32 v[184:185], s[2:3], s1, v193, v[116:117]
	global_load_dwordx4 v[16:19], v[184:185], off
	v_max_i32_e32 v155, 0, v205
	v_pk_fma_f32 v[156:157], v[108:109], v[56:57], v[156:157]
	v_pk_fma_f32 v[156:157], v[110:111], v[60:61], v[156:157]
	v_pk_fma_f32 v[156:157], v[112:113], v[64:65], v[156:157]
	v_pk_fma_f32 v[156:157], v[114:115], v[154:155], v[156:157]
	v_bfe_u32 v56, v157, 19, 12
	v_bfe_u32 v64, v156, 19, 12
	v_med3_u32 v56, v56, s94, v194
	v_med3_u32 v64, v64, s94, v194
	s_waitcnt lgkmcnt(6)
	v_mfma_f32_32x32x16_bf16 v[0:15], v[38:41], v[230:233], v[0:15]
	v_sub_u32_e32 v57, 0x86f, v56
	v_add_u32_e32 v60, 0xfffffb90, v56
	v_sub_u32_e32 v65, 0x86f, v64
	v_add_u32_e32 v154, 0xfffffb90, v64
	v_cmp_gt_f32_e32 vcc, 0, v157
	s_nop 1
	v_cndmask_b32_e32 v56, v60, v57, vcc
	v_cmp_gt_f32_e32 vcc, 0, v156
	v_lshl_add_u32 v61, v56, 2, v33
	s_waitcnt lgkmcnt(5)
	v_mfma_f32_32x32x16_bf16 v[160:175], v[38:41], v[234:237], v[160:175]
	ds_add_u32 v61, v188
	v_cndmask_b32_e32 v64, v154, v65, vcc
	v_lshl_add_u32 v155, v64, 2, v33
	ds_add_u32 v155, v188 offset:4096
	v_max_i32_e32 v56, 0, v222
	v_max_i32_e32 v57, 0, v214
	v_max_i32_e32 v60, 0, v223
	v_max_i32_e32 v61, 0, v215
	v_max_i32_e32 v64, 0, v224
	s_waitcnt lgkmcnt(6)
	v_mfma_f32_32x32x16_bf16 v[0:15], v[42:45], v[238:241], v[0:15]
	v_max_i32_e32 v65, 0, v216
	v_max_i32_e32 v154, 0, v225
	v_max_i32_e32 v155, 0, v217
	v_pk_fma_f32 v[156:157], v[100:101], v[56:57], 0 op_sel_hi:[1,1,0]
	v_pk_fma_f32 v[156:157], v[102:103], v[60:61], v[156:157]
	v_pk_fma_f32 v[156:157], v[104:105], v[64:65], v[156:157]
	v_pk_fma_f32 v[156:157], v[106:107], v[154:155], v[156:157]
	v_max_i32_e32 v56, 0, v226
	v_max_i32_e32 v57, 0, v218
	s_waitcnt lgkmcnt(5)
	v_mfma_f32_32x32x16_bf16 v[160:175], v[42:45], v[242:245], v[160:175]
	v_max_i32_e32 v60, 0, v227
	v_max_i32_e32 v61, 0, v219
	v_max_i32_e32 v64, 0, v228
	v_max_i32_e32 v65, 0, v220
	v_max_i32_e32 v154, 0, v229
	v_max_i32_e32 v155, 0, v221
	v_pk_fma_f32 v[156:157], v[108:109], v[56:57], v[156:157]
	v_pk_fma_f32 v[156:157], v[110:111], v[60:61], v[156:157]
	v_pk_fma_f32 v[156:157], v[112:113], v[64:65], v[156:157]
	s_waitcnt lgkmcnt(4)
	v_mfma_f32_32x32x16_bf16 v[0:15], v[46:49], v[246:249], v[0:15]
	v_pk_fma_f32 v[156:157], v[114:115], v[154:155], v[156:157]
	v_bfe_u32 v56, v157, 19, 12
	v_bfe_u32 v64, v156, 19, 12
	v_med3_u32 v56, v56, s94, v194
	v_med3_u32 v64, v64, s94, v194
	v_sub_u32_e32 v57, 0x86f, v56
	v_add_u32_e32 v60, 0xfffffb90, v56
	v_sub_u32_e32 v65, 0x86f, v64
	v_add_u32_e32 v154, 0xfffffb90, v64
	s_waitcnt lgkmcnt(3)
	v_mfma_f32_32x32x16_bf16 v[160:175], v[46:49], v[50:53], v[160:175]
	v_cmp_gt_f32_e32 vcc, 0, v157
	s_nop 1
	v_cndmask_b32_e32 v56, v60, v57, vcc
	v_cmp_gt_f32_e32 vcc, 0, v156
	v_lshl_add_u32 v61, v56, 2, v33
	ds_add_u32 v61, v188
	v_cndmask_b32_e32 v64, v154, v65, vcc
	v_lshl_add_u32 v155, v64, 2, v33
	ds_add_u32 v155, v188 offset:4096
	s_waitcnt lgkmcnt(0)
	s_barrier
	s_add_u32 s0, s0, 1
	s_cmp_ge_u32 s0, s13
	s_cbranch_scc1 .Lp1_drain0
	s_branch .Lp1_c1
.Lp1_drain0:
	v_max_i32_e32 v56, 0, v8
	v_max_i32_e32 v57, 0, v0
	v_max_i32_e32 v60, 0, v9
	v_max_i32_e32 v61, 0, v1
	v_max_i32_e32 v64, 0, v10
	v_max_i32_e32 v65, 0, v2
	v_max_i32_e32 v154, 0, v11
	v_max_i32_e32 v155, 0, v3
	v_pk_fma_f32 v[156:157], v[100:101], v[56:57], 0 op_sel_hi:[1,1,0]
	v_pk_fma_f32 v[156:157], v[102:103], v[60:61], v[156:157]
	v_pk_fma_f32 v[156:157], v[104:105], v[64:65], v[156:157]
	v_pk_fma_f32 v[156:157], v[106:107], v[154:155], v[156:157]
	v_max_i32_e32 v56, 0, v12
	v_max_i32_e32 v57, 0, v4
	v_max_i32_e32 v60, 0, v13
	v_max_i32_e32 v61, 0, v5
	v_max_i32_e32 v64, 0, v14
	v_max_i32_e32 v65, 0, v6
	v_max_i32_e32 v154, 0, v15
	v_max_i32_e32 v155, 0, v7
	v_pk_fma_f32 v[156:157], v[108:109], v[56:57], v[156:157]
	v_pk_fma_f32 v[156:157], v[110:111], v[60:61], v[156:157]
	v_pk_fma_f32 v[156:157], v[112:113], v[64:65], v[156:157]
	v_pk_fma_f32 v[156:157], v[114:115], v[154:155], v[156:157]
	v_bfe_u32 v56, v157, 19, 12
	v_bfe_u32 v64, v156, 19, 12
	v_med3_u32 v56, v56, s94, v194
	v_med3_u32 v64, v64, s94, v194
	v_sub_u32_e32 v57, 0x86f, v56
	v_add_u32_e32 v60, 0xfffffb90, v56
	v_sub_u32_e32 v65, 0x86f, v64
	v_add_u32_e32 v154, 0xfffffb90, v64
	v_cmp_gt_f32_e32 vcc, 0, v157
	s_nop 1
	v_cndmask_b32_e32 v56, v60, v57, vcc
	v_cmp_gt_f32_e32 vcc, 0, v156
	v_lshl_add_u32 v61, v56, 2, v33
	ds_add_u32 v61, v188
	v_cndmask_b32_e32 v64, v154, v65, vcc
	v_lshl_add_u32 v155, v64, 2, v33
	ds_add_u32 v155, v188 offset:4096
	v_max_i32_e32 v56, 0, v168
	v_max_i32_e32 v57, 0, v160
	v_max_i32_e32 v60, 0, v169
	v_max_i32_e32 v61, 0, v161
	v_max_i32_e32 v64, 0, v170
	v_max_i32_e32 v65, 0, v162
	v_max_i32_e32 v154, 0, v171
	v_max_i32_e32 v155, 0, v163
	v_pk_fma_f32 v[156:157], v[100:101], v[56:57], 0 op_sel_hi:[1,1,0]
	v_pk_fma_f32 v[156:157], v[102:103], v[60:61], v[156:157]
	v_pk_fma_f32 v[156:157], v[104:105], v[64:65], v[156:157]
	v_pk_fma_f32 v[156:157], v[106:107], v[154:155], v[156:157]
	v_max_i32_e32 v56, 0, v172
	v_max_i32_e32 v57, 0, v164
	v_max_i32_e32 v60, 0, v173
	v_max_i32_e32 v61, 0, v165
	v_max_i32_e32 v64, 0, v174
	v_max_i32_e32 v65, 0, v166
	v_max_i32_e32 v154, 0, v175
	v_max_i32_e32 v155, 0, v167
	v_pk_fma_f32 v[156:157], v[108:109], v[56:57], v[156:157]
	v_pk_fma_f32 v[156:157], v[110:111], v[60:61], v[156:157]
	v_pk_fma_f32 v[156:157], v[112:113], v[64:65], v[156:157]
	v_pk_fma_f32 v[156:157], v[114:115], v[154:155], v[156:157]
	v_bfe_u32 v56, v157, 19, 12
	v_bfe_u32 v64, v156, 19, 12
	v_med3_u32 v56, v56, s94, v194
	v_med3_u32 v64, v64, s94, v194
	v_sub_u32_e32 v57, 0x86f, v56
	v_add_u32_e32 v60, 0xfffffb90, v56
	v_sub_u32_e32 v65, 0x86f, v64
	v_add_u32_e32 v154, 0xfffffb90, v64
	v_cmp_gt_f32_e32 vcc, 0, v157
	s_nop 1
	v_cndmask_b32_e32 v56, v60, v57, vcc
	v_cmp_gt_f32_e32 vcc, 0, v156
	v_lshl_add_u32 v61, v56, 2, v33
	ds_add_u32 v61, v188
	v_cndmask_b32_e32 v64, v154, v65, vcc
	v_lshl_add_u32 v155, v64, 2, v33
	ds_add_u32 v155, v188 offset:4096
	s_branch .LBB0_904
.Lp1_drain1:
	v_max_i32_e32 v56, 0, v206
	v_max_i32_e32 v57, 0, v198
	v_max_i32_e32 v60, 0, v207
	v_max_i32_e32 v61, 0, v199
	v_max_i32_e32 v64, 0, v208
	v_max_i32_e32 v65, 0, v200
	v_max_i32_e32 v154, 0, v209
	v_max_i32_e32 v155, 0, v201
	v_pk_fma_f32 v[156:157], v[100:101], v[56:57], 0 op_sel_hi:[1,1,0]
	v_pk_fma_f32 v[156:157], v[102:103], v[60:61], v[156:157]
	v_pk_fma_f32 v[156:157], v[104:105], v[64:65], v[156:157]
	v_pk_fma_f32 v[156:157], v[106:107], v[154:155], v[156:157]
	v_max_i32_e32 v56, 0, v210
	v_max_i32_e32 v57, 0, v202
	v_max_i32_e32 v60, 0, v211
	v_max_i32_e32 v61, 0, v203
	v_max_i32_e32 v64, 0, v212
	v_max_i32_e32 v65, 0, v204
	v_max_i32_e32 v154, 0, v213
	v_max_i32_e32 v155, 0, v205
	v_pk_fma_f32 v[156:157], v[108:109], v[56:57], v[156:157]
	v_pk_fma_f32 v[156:157], v[110:111], v[60:61], v[156:157]
	v_pk_fma_f32 v[156:157], v[112:113], v[64:65], v[156:157]
	v_pk_fma_f32 v[156:157], v[114:115], v[154:155], v[156:157]
	v_bfe_u32 v56, v157, 19, 12
	v_bfe_u32 v64, v156, 19, 12
	v_med3_u32 v56, v56, s94, v194
	v_med3_u32 v64, v64, s94, v194
	v_sub_u32_e32 v57, 0x86f, v56
	v_add_u32_e32 v60, 0xfffffb90, v56
	v_sub_u32_e32 v65, 0x86f, v64
	v_add_u32_e32 v154, 0xfffffb90, v64
	v_cmp_gt_f32_e32 vcc, 0, v157
	s_nop 1
	v_cndmask_b32_e32 v56, v60, v57, vcc
	v_cmp_gt_f32_e32 vcc, 0, v156
	v_lshl_add_u32 v61, v56, 2, v33
	ds_add_u32 v61, v188
	v_cndmask_b32_e32 v64, v154, v65, vcc
	v_lshl_add_u32 v155, v64, 2, v33
	ds_add_u32 v155, v188 offset:4096
	v_max_i32_e32 v56, 0, v222
	v_max_i32_e32 v57, 0, v214
	v_max_i32_e32 v60, 0, v223
	v_max_i32_e32 v61, 0, v215
	v_max_i32_e32 v64, 0, v224
	v_max_i32_e32 v65, 0, v216
	v_max_i32_e32 v154, 0, v225
	v_max_i32_e32 v155, 0, v217
	v_pk_fma_f32 v[156:157], v[100:101], v[56:57], 0 op_sel_hi:[1,1,0]
	v_pk_fma_f32 v[156:157], v[102:103], v[60:61], v[156:157]
	v_pk_fma_f32 v[156:157], v[104:105], v[64:65], v[156:157]
	v_pk_fma_f32 v[156:157], v[106:107], v[154:155], v[156:157]
	v_max_i32_e32 v56, 0, v226
	v_max_i32_e32 v57, 0, v218
	v_max_i32_e32 v60, 0, v227
	v_max_i32_e32 v61, 0, v219
	v_max_i32_e32 v64, 0, v228
	v_max_i32_e32 v65, 0, v220
	v_max_i32_e32 v154, 0, v229
	v_max_i32_e32 v155, 0, v221
	v_pk_fma_f32 v[156:157], v[108:109], v[56:57], v[156:157]
	v_pk_fma_f32 v[156:157], v[110:111], v[60:61], v[156:157]
	v_pk_fma_f32 v[156:157], v[112:113], v[64:65], v[156:157]
	v_pk_fma_f32 v[156:157], v[114:115], v[154:155], v[156:157]
	v_bfe_u32 v56, v157, 19, 12
	v_bfe_u32 v64, v156, 19, 12
	v_med3_u32 v56, v56, s94, v194
	v_med3_u32 v64, v64, s94, v194
	v_sub_u32_e32 v57, 0x86f, v56
	v_add_u32_e32 v60, 0xfffffb90, v56
	v_sub_u32_e32 v65, 0x86f, v64
	v_add_u32_e32 v154, 0xfffffb90, v64
	v_cmp_gt_f32_e32 vcc, 0, v157
	s_nop 1
	v_cndmask_b32_e32 v56, v60, v57, vcc
	v_cmp_gt_f32_e32 vcc, 0, v156
	v_lshl_add_u32 v61, v56, 2, v33
	ds_add_u32 v61, v188
	v_cndmask_b32_e32 v64, v154, v65, vcc
	v_lshl_add_u32 v155, v64, 2, v33
	ds_add_u32 v155, v188 offset:4096
	s_branch .LBB0_904
